# dead c1/c2 reduction chains removed from the scan producer (144 instructions, hazard nops re-inserted)
# baseline (speedup 1.0000x reference)
; __device__ __forceinline__ void scan_issue(ScanRegs& R, const bf16_t* PRKV, const unsigned short* WLOG, const bf16_t* ASIG, size_t tok, int ch, int want_prev) {
;     const bf16_t* pp = PRKV + tok * 3072 + ch;
;     R.pr = *(const u32x2*)pp; R.pk = *(const u32x2*)(pp + 1024); R.pv = *(const u32x2*)(pp + 2048);
;     R.qr = (u32x2){0u, 0u}; R.qk = (u32x2){0u, 0u}; R.qv = (u32x2){0u, 0u};
;     if (want_prev == 1) { R.qr = *(const u32x2*)(pp - 3072); R.qk = *(const u32x2*)(pp - 3072 + 1024); R.qv = *(const u32x2*)(pp - 3072 + 2048); }
;     R.wl = *(const u32x2*)(WLOG + tok * 1024 + ch); R.as = *(const u32x2*)(ASIG + tok * 1024 + ch);
; }
; __device__ __forceinline__ void unpack4(const u32x2 u, float (&f)[4]) { f[0] = lo_bf(u.x); f[1] = hi_bf(u.x); f[2] = lo_bf(u.y); f[3] = hi_bf(u.y); }
; __device__ __forceinline__ float scan_prepare(const ScanRegs& R, const u32x2 qr_, const u32x2 qk_, const u32x2 qv_, LAS float* slot, int cq, const f32x4 mur, const f32x4 muk, const f32x4 muv, const f32x4 kkc, const f32x4 kac, const f32x4 rkc) {
;     float pr[4], pk[4], pv[4], qr[4], qk[4], qv[4], av[4], om[4];
;     unpack4(R.pr, pr); unpack4(R.pk, pk); unpack4(R.pv, pv); unpack4(qr_, qr); unpack4(qk_, qk); unpack4(qv_, qv); unpack4(R.as, av);
;     om[0] = f16_to_f((unsigned short)(R.wl.x & 0xffffu)); om[1] = f16_to_f((unsigned short)(R.wl.x >> 16)); om[2] = f16_to_f((unsigned short)(R.wl.y & 0xffffu)); om[3] = f16_to_f((unsigned short)(R.wl.y >> 16));
;     float rr[4], vv[4], kn[4], k2[4], dec[4], bu[4];
; __device__ __forceinline__ void p8_scan(const Args& a, LAS unsigned char* lds) {
;     ...
;             { const size_t tok = (size_t)b * T + 2 * ltt; scan_issue(A0, PRKV, WLOG, ASIG, tok, ch, ltt > 0 ? 1 : 2); scan_issue(A1, PRKV, WLOG, ASIG, tok + 1, ch, 0);
;               const float b0 = scan_prepare(A0, A0.qr, A0.qk, A0.qv, buf + (2 * ltt) * SPITCH, cq, mur, muk, muv, kkc, kac, rkc);
;               const float b1 = scan_prepare(A1, A0.pr, A0.pk, A0.pv, buf + (2 * ltt + 1) * SPITCH, cq, mur, muk, muv, kkc, kac, rkc);
;               if (rq == 0 && cq == 0) { BONUS[tok * 16 + h] = b0; BONUS[(tok + 1) * 16 + h] = b1; }
;               scan_issue(A0, PRKV, WLOG, ASIG, tok + TC, ch, 1); scan_issue(A1, PRKV, WLOG, ASIG, tok + TC + 1, ch, 0);
;               scan_issue(B0, PRKV, WLOG, ASIG, tok + 2 * TC, ch, 1); scan_issue(B1, PRKV, WLOG, ASIG, tok + 2 * TC + 1, ch, 0); }
.LBB0_1097:
	s_or_b64 exec, exec, s[44:45]
	v_lshlrev_b32_e32 v32, 11, v139
	v_mov_b32_e32 v33, v29
	v_lshl_add_u64 v[42:43], s[90:91], 0, v[32:33]
	v_lshl_add_u64 v[42:43], v[42:43], 0, v[28:29]
	global_load_dwordx2 v[60:61], v[42:43], off
	v_lshl_add_u64 v[36:37], s[8:9], 0, v[32:33]
	v_lshl_add_u64 v[36:37], v[36:37], 0, v[28:29]
	s_mov_b64 s[44:45], 0x1800
	global_load_dwordx2 v[62:63], v[36:37], off
	v_or_b32_e32 v1, 1, v139
	s_waitcnt vmcnt(3)
	v_lshlrev_b32_e32 v46, 16, v38
	v_and_b32_e32 v47, 0xffff0000, v38
	s_waitcnt vmcnt(2)
	v_lshlrev_b32_e32 v36, 16, v52
	v_and_b32_e32 v37, 0xffff0000, v52
	v_lshlrev_b32_e32 v44, 16, v39
	v_and_b32_e32 v45, 0xffff0000, v39
	v_lshlrev_b32_e32 v38, 16, v53
	v_and_b32_e32 v39, 0xffff0000, v53
	v_lshlrev_b32_e32 v52, 16, v55
	v_and_b32_e32 v53, 0xffff0000, v55
	v_lshl_add_u64 v[34:35], v[34:35], 0, s[44:45]
	v_mov_b32_e32 v57, v29
	v_lshlrev_b32_e32 v58, 16, v54
	v_and_b32_e32 v59, 0xffff0000, v54
	v_lshlrev_b32_e32 v54, 16, v50
	v_and_b32_e32 v55, 0xffff0000, v50
	v_lshlrev_b32_e32 v50, 16, v51
	v_and_b32_e32 v51, 0xffff0000, v51
	s_movk_i32 s43, 0x1000
	v_lshlrev_b32_e32 v56, 11, v1
	v_pk_add_f32 v[52:53], v[52:53], v[38:39] neg_lo:[0,1] neg_hi:[0,1]
	v_lshl_add_u64 v[72:73], v[34:35], 0, v[28:29]
	v_lshlrev_b32_e32 v42, 16, v40
	v_and_b32_e32 v43, 0xffff0000, v40
	v_lshlrev_b32_e32 v64, 16, v48
	v_and_b32_e32 v65, 0xffff0000, v48
	v_pk_add_f32 v[70:71], v[50:51], v[44:45] neg_lo:[0,1] neg_hi:[0,1]
	v_lshl_add_u64 v[50:51], s[8:9], 0, v[56:57]
	v_lshl_add_u64 v[56:57], s[90:91], 0, v[56:57]
	v_pk_fma_f32 v[66:67], v[8:9], v[52:53], v[38:39]
	v_add_co_u32_e32 v52, vcc, s43, v72
	v_pk_add_f32 v[58:59], v[58:59], v[36:37] neg_lo:[0,1] neg_hi:[0,1]
	v_pk_add_f32 v[54:55], v[54:55], v[46:47] neg_lo:[0,1] neg_hi:[0,1]
	v_pk_add_f32 v[68:69], v[64:65], v[42:43] neg_lo:[0,1] neg_hi:[0,1]
	v_addc_co_u32_e32 v53, vcc, 0, v73, vcc
	v_lshl_add_u64 v[56:57], v[56:57], 0, v[28:29]
	v_pk_fma_f32 v[64:65], v[6:7], v[58:59], v[36:37]
	v_pk_fma_f32 v[74:75], v[2:3], v[54:55], v[46:47]
	v_pk_fma_f32 v[84:85], v[10:11], v[68:69], v[42:43]
	v_lshl_add_u64 v[68:69], v[50:51], 0, v[28:29]
	global_load_dwordx2 v[50:51], v[72:73], off
	global_load_dwordx2 v[54:55], v[72:73], off offset:2048
	global_load_dwordx2 v[58:59], v[52:53], off
	s_nop 0
	global_load_dwordx2 v[52:53], v[68:69], off
	s_nop 0
	global_load_dwordx2 v[56:57], v[56:57], off
	v_pk_fma_f32 v[70:71], v[4:5], v[70:71], v[44:45]
	v_pk_mul_f32 v[76:77], v[14:15], v[74:75]
	v_pk_mul_f32 v[78:79], v[16:17], v[70:71]
	v_pk_mul_f32 v[68:69], v[76:77], v[76:77]
	v_pk_mul_f32 v[72:73], v[78:79], v[78:79]
	v_add_f32_e32 v33, v68, v69
	v_add_f32_e32 v33, v72, v33
	v_add_f32_e32 v33, v73, v33
	v_lshlrev_b32_e32 v40, 16, v41
	v_and_b32_e32 v41, 0xffff0000, v41
	v_add_f32_dpp v33, v33, v33 row_ror:1 row_mask:0xf bank_mask:0xf bound_ctrl:1
	s_waitcnt vmcnt(6)
	v_lshlrev_b32_e32 v68, 16, v60
	v_and_b32_e32 v69, 0xffff0000, v60
	v_pk_add_f32 v[80:81], v[68:69], -1.0 op_sel_hi:[1,0]
	v_add_f32_dpp v33, v33, v33 row_ror:2 row_mask:0xf bank_mask:0xf bound_ctrl:1
	v_pk_mul_f32 v[86:87], v[76:77], v[68:69]
	v_pk_fma_f32 v[68:69], v[18:19], v[80:81], 1.0 op_sel_hi:[1,1,0]
	v_add_f32_dpp v33, v33, v33 row_ror:4 row_mask:0xf bank_mask:0xf bound_ctrl:1
	v_pk_mul_f32 v[68:69], v[74:75], v[68:69]
	s_nop 0
	v_add_f32_dpp v33, v33, v33 row_ror:8 row_mask:0xf bank_mask:0xf bound_ctrl:1
	v_pk_mul_f32 v[74:75], v[84:85], v[68:69]
	v_max_f32_e32 v33, 0x179abe15, v33
	v_lshlrev_b32_e32 v60, 16, v61
	v_and_b32_e32 v61, 0xffff0000, v61
	v_pk_add_f32 v[82:83], v[60:61], -1.0 op_sel_hi:[1,0]
	v_fma_f32 v91, v22, v74, 0
	v_rsq_f32_e32 v48, v33
	v_fmac_f32_e32 v91, v23, v75
	v_pk_fma_f32 v[74:75], v[20:21], v[82:83], 1.0 op_sel_hi:[1,1,0]
	v_pk_mul_f32 v[60:61], v[78:79], v[60:61]
	v_pk_mul_f32 v[70:71], v[70:71], v[74:75]
	v_lshlrev_b32_e32 v74, 16, v49
	v_and_b32_e32 v75, 0xffff0000, v49
	v_pk_add_f32 v[74:75], v[74:75], v[40:41] neg_lo:[0,1] neg_hi:[0,1]
	v_pk_mul_f32 v[80:81], v[86:87], v[48:49] op_sel_hi:[1,0]
	v_pk_fma_f32 v[86:87], v[12:13], v[74:75], v[40:41]
	s_waitcnt vmcnt(5)
	v_cvt_f32_f16_e32 v72, v62
	v_cvt_f32_f16_sdwa v73, v62 dst_sel:DWORD dst_unused:UNUSED_PAD src0_sel:WORD_1
	v_pk_mul_f32 v[82:83], v[60:61], v[48:49] op_sel_hi:[1,0]
	v_cvt_f32_f16_e32 v62, v63
	v_cvt_f32_f16_sdwa v63, v63 dst_sel:DWORD dst_unused:UNUSED_PAD src0_sel:WORD_1
	v_pk_mul_f32 v[88:89], v[86:87], v[70:71]
	v_pk_mul_f32 v[78:79], v[78:79], v[48:49] op_sel_hi:[1,0] neg_lo:[0,1] neg_hi:[0,1]
	v_pk_mul_f32 v[76:77], v[76:77], v[48:49] op_sel_hi:[1,0] neg_lo:[0,1] neg_hi:[0,1]
	v_fmac_f32_e32 v91, v24, v88
	v_fmac_f32_e32 v91, v25, v89
	s_nop 0
	s_nop 0
	v_add_f32_dpp v60, v91, v91 row_ror:1 row_mask:0xf bank_mask:0xf bound_ctrl:1
	v_pk_add_f32 v[74:75], v[62:63], 1.0 op_sel_hi:[1,0] neg_lo:[1,0] neg_hi:[1,0]
	s_nop 0
	v_add_f32_dpp v60, v60, v60 row_ror:2 row_mask:0xf bank_mask:0xf bound_ctrl:1
	s_nop 1
	v_add_f32_dpp v33, v60, v60 row_ror:4 row_mask:0xf bank_mask:0xf bound_ctrl:1
	v_mov_b32_e32 v49, v29
	v_pk_add_f32 v[72:73], v[72:73], 1.0 op_sel_hi:[1,0] neg_lo:[1,0] neg_hi:[1,0]
	s_nop 0
	v_mov_b32_dpp v49, v33 row_ror:8 row_mask:0xf bank_mask:0xf
	v_pk_mul_f32 v[84:85], v[84:85], 1.0 op_sel_hi:[1,0]
	v_pk_mul_f32 v[86:87], v[86:87], 1.0 op_sel_hi:[1,0]
	ds_write_b128 v127, v[72:75]
	ds_write_b128 v127, v[68:71] offset:256
	ds_write_b128 v127, v[76:79] offset:512
	ds_write_b128 v127, v[80:83] offset:768
	ds_write_b128 v127, v[84:87] offset:1024
	ds_write_b128 v127, v[64:67] offset:1280
	s_and_saveexec_b64 s[44:45], s[4:5]
	s_or_b64 exec, exec, s[44:45]
	s_waitcnt vmcnt(2)
; __device__ __forceinline__ float scan_prepare(const ScanRegs& R, const u32x2 qr_, const u32x2 qk_, const u32x2 qv_, LAS float* slot, int cq, const f32x4 mur, const f32x4 muk, const f32x4 muv, const f32x4 kkc, const f32x4 kac, const f32x4 rkc) {
;     float pr[4], pk[4], pv[4], qr[4], qk[4], qv[4], av[4], om[4];
;     unpack4(R.pr, pr); unpack4(R.pk, pk); unpack4(R.pv, pv); unpack4(qr_, qr); unpack4(qk_, qk); unpack4(qv_, qv); unpack4(R.as, av);
;     om[0] = f16_to_f((unsigned short)(R.wl.x & 0xffffu)); om[1] = f16_to_f((unsigned short)(R.wl.x >> 16)); om[2] = f16_to_f((unsigned short)(R.wl.y & 0xffffu)); om[3] = f16_to_f((unsigned short)(R.wl.y >> 16));
;     float rr[4], vv[4], kn[4], k2[4], dec[4], bu[4];
;     float ssq = 0.f, bon = 0.f, c1 = 0.f, c2 = 0.f;
; #pragma unroll
;     for (int j = 0; j < 4; ++j) {
;         rr[j] = pr[j] + (qr[j] - pr[j]) * mur[j]; const float kk0 = pk[j] + (qk[j] - pk[j]) * muk[j]; vv[j] = pv[j] + (qv[j] - pv[j]) * muv[j];
;         dec[j] = 1.0f - om[j];
;         kn[j] = kk0 * kkc[j]; ssq += kn[j] * kn[j];
;         k2[j] = kk0 * (1.0f + (av[j] - 1.0f) * kac[j]);
;         const float t = rr[j] * k2[j]; bon += t * rkc[j]; c2 += t;
;         bu[j] = kn[j] * av[j]; c1 += bu[j] * rr[j];
;     }
;     ssq += dpp_f<0x121>(ssq); bon += dpp_f<0x121>(bon); c1 += dpp_f<0x121>(c1); c2 += dpp_f<0x121>(c2);
;     ssq += dpp_f<0x122>(ssq); bon += dpp_f<0x122>(bon); c1 += dpp_f<0x122>(c1); c2 += dpp_f<0x122>(c2);
;     ssq += dpp_f<0x124>(ssq); bon += dpp_f<0x124>(bon); c1 += dpp_f<0x124>(c1); c2 += dpp_f<0x124>(c2);
;     ssq += dpp_f<0x128>(ssq); bon += dpp_f<0x128>(bon); c1 += dpp_f<0x128>(c1); c2 += dpp_f<0x128>(c2);
; __device__ __forceinline__ void p8_scan(const Args& a, LAS unsigned char* lds) {
;     ...
;               const float b0 = scan_prepare(A0, A0.qr, A0.qk, A0.qv, buf + (2 * ltt) * SPITCH, cq, mur, muk, muv, kkc, kac, rkc);
;               const float b1 = scan_prepare(A1, A0.pr, A0.pk, A0.pv, buf + (2 * ltt + 1) * SPITCH, cq, mur, muk, muv, kkc, kac, rkc);
;               if (rq == 0 && cq == 0) { BONUS[tok * 16 + h] = b0; BONUS[(tok + 1) * 16 + h] = b1; }
;               scan_issue(A0, PRKV, WLOG, ASIG, tok + TC, ch, 1); scan_issue(A1, PRKV, WLOG, ASIG, tok + TC + 1, ch, 0);
;               scan_issue(B0, PRKV, WLOG, ASIG, tok + 2 * TC, ch, 1); scan_issue(B1, PRKV, WLOG, ASIG, tok + 2 * TC + 1, ch, 0); }
	v_lshlrev_b32_e32 v70, 16, v58
	v_and_b32_e32 v71, 0xffff0000, v58
	v_lshlrev_b32_e32 v72, 16, v59
	v_and_b32_e32 v73, 0xffff0000, v59
	v_lshlrev_b32_e32 v58, 16, v54
	v_and_b32_e32 v59, 0xffff0000, v54
	v_pk_add_f32 v[46:47], v[46:47], v[58:59] neg_lo:[0,1] neg_hi:[0,1]
	s_waitcnt vmcnt(0)
	v_lshlrev_b32_e32 v60, 16, v56
	v_pk_fma_f32 v[46:47], v[2:3], v[46:47], v[58:59]
	v_and_b32_e32 v61, 0xffff0000, v56
	v_pk_mul_f32 v[64:65], v[14:15], v[46:47]
	v_pk_add_f32 v[58:59], v[60:61], -1.0 op_sel_hi:[1,0]
	v_pk_mul_f32 v[74:75], v[64:65], v[60:61]
	v_lshlrev_b32_e32 v60, 16, v50
	v_and_b32_e32 v61, 0xffff0000, v50
	v_pk_fma_f32 v[58:59], v[18:19], v[58:59], 1.0 op_sel_hi:[1,1,0]
	v_pk_add_f32 v[42:43], v[42:43], v[60:61] neg_lo:[0,1] neg_hi:[0,1]
	v_pk_mul_f32 v[58:59], v[46:47], v[58:59]
	v_pk_fma_f32 v[76:77], v[10:11], v[42:43], v[60:61]
	v_pk_mul_f32 v[66:67], v[64:65], v[64:65]
	v_pk_mul_f32 v[42:43], v[76:77], v[58:59]
	v_cvt_f32_f16_sdwa v47, v52 dst_sel:DWORD dst_unused:UNUSED_PAD src0_sel:WORD_1
	v_fma_f32 v48, v22, v42, 0
	v_fmac_f32_e32 v48, v23, v43
	v_lshlrev_b32_e32 v42, 16, v55
	v_and_b32_e32 v43, 0xffff0000, v55
	v_pk_add_f32 v[44:45], v[44:45], v[42:43] neg_lo:[0,1] neg_hi:[0,1]
	v_cvt_f32_f16_e32 v46, v52
	v_pk_fma_f32 v[44:45], v[4:5], v[44:45], v[42:43]
	v_add_f32_e32 v50, v66, v67
	v_pk_mul_f32 v[54:55], v[16:17], v[44:45]
	v_pk_add_f32 v[62:63], v[46:47], 1.0 op_sel_hi:[1,0] neg_lo:[1,0] neg_hi:[1,0]
	v_pk_mul_f32 v[42:43], v[54:55], v[54:55]
	v_add_f32_e32 v42, v42, v50
	v_add_f32_e32 v42, v43, v42
	s_nop 0
	s_nop 0
	v_add_f32_dpp v42, v42, v42 row_ror:1 row_mask:0xf bank_mask:0xf bound_ctrl:1
	v_lshlrev_b32_e32 v46, 16, v57
	v_and_b32_e32 v47, 0xffff0000, v57
	v_add_f32_dpp v42, v42, v42 row_ror:2 row_mask:0xf bank_mask:0xf bound_ctrl:1
	v_pk_add_f32 v[56:57], v[46:47], -1.0 op_sel_hi:[1,0]
	v_cvt_f32_f16_e32 v50, v53
	v_add_f32_dpp v42, v42, v42 row_ror:4 row_mask:0xf bank_mask:0xf bound_ctrl:1
	v_pk_fma_f32 v[56:57], v[20:21], v[56:57], 1.0 op_sel_hi:[1,1,0]
	v_pk_add_f32 v[36:37], v[36:37], v[70:71] neg_lo:[0,1] neg_hi:[0,1]
	v_add_f32_dpp v42, v42, v42 row_ror:8 row_mask:0xf bank_mask:0xf bound_ctrl:1
	v_max_f32_e32 v42, 0x179abe15, v42
	v_rsq_f32_e32 v42, v42
	v_pk_mul_f32 v[60:61], v[44:45], v[56:57]
	v_pk_mul_f32 v[44:45], v[54:55], v[46:47]
	v_lshlrev_b32_e32 v46, 16, v51
	v_and_b32_e32 v47, 0xffff0000, v51
	v_pk_add_f32 v[40:41], v[40:41], v[46:47] neg_lo:[0,1] neg_hi:[0,1]
	v_cvt_f32_f16_sdwa v51, v53 dst_sel:DWORD dst_unused:UNUSED_PAD src0_sel:WORD_1
	v_pk_fma_f32 v[52:53], v[12:13], v[40:41], v[46:47]
	v_pk_mul_f32 v[68:69], v[44:45], v[42:43] op_sel_hi:[1,0]
	v_pk_mul_f32 v[40:41], v[52:53], v[60:61]
	v_pk_mul_f32 v[56:57], v[54:55], v[42:43] op_sel_hi:[1,0] neg_lo:[0,1] neg_hi:[0,1]
	v_pk_mul_f32 v[54:55], v[64:65], v[42:43] op_sel_hi:[1,0] neg_lo:[0,1] neg_hi:[0,1]
	v_pk_mul_f32 v[66:67], v[74:75], v[42:43] op_sel_hi:[1,0]
	v_fmac_f32_e32 v48, v24, v40
	v_fmac_f32_e32 v48, v25, v41
	s_nop 0
	s_nop 0
	v_add_f32_dpp v43, v48, v48 row_ror:1 row_mask:0xf bank_mask:0xf bound_ctrl:1
	s_nop 1
	v_add_f32_dpp v43, v43, v43 row_ror:2 row_mask:0xf bank_mask:0xf bound_ctrl:1
	s_nop 1
	v_add_f32_dpp v40, v43, v43 row_ror:4 row_mask:0xf bank_mask:0xf bound_ctrl:1
	v_mov_b32_e32 v41, v29
	v_pk_add_f32 v[38:39], v[38:39], v[72:73] neg_lo:[0,1] neg_hi:[0,1]
	v_pk_add_f32 v[64:65], v[50:51], 1.0 op_sel_hi:[1,0] neg_lo:[1,0] neg_hi:[1,0]
	v_mov_b32_dpp v41, v40 row_ror:8 row_mask:0xf bank_mask:0xf
	v_pk_fma_f32 v[38:39], v[8:9], v[38:39], v[72:73]
	v_pk_fma_f32 v[36:37], v[6:7], v[36:37], v[70:71]
	v_pk_mul_f32 v[50:51], v[76:77], 1.0 op_sel_hi:[1,0]
	v_pk_mul_f32 v[52:53], v[52:53], 1.0 op_sel_hi:[1,0]
	ds_write_b128 v129, v[62:65]
	ds_write_b128 v129, v[58:61] offset:256
	ds_write_b128 v129, v[54:57] offset:512
	ds_write_b128 v129, v[66:69] offset:768
	ds_write_b128 v129, v[50:53] offset:1024
	ds_write_b128 v129, v[36:39] offset:1280
	s_and_saveexec_b64 s[44:45], s[4:5]
	s_mov_b64 s[84:85], s[56:57]
	s_or_b64 exec, exec, s[44:45]
	s_cmp_lt_u32 s71, 64
	s_cselect_b64 s[44:45], -1, 0
	s_and_b64 s[44:45], s[4:5], s[44:45]
	s_xor_b64 s[52:53], s[44:45], -1
	v_mov_b64_e32 v[100:101], s[14:15]
	s_and_saveexec_b64 s[56:57], s[52:53]
	s_xor_b64 s[52:53], exec, s[56:57]
	v_mov_b64_e32 v[100:101], s[14:15]
	s_andn2_saveexec_b64 s[52:53], s[52:53]
	s_cbranch_execz .LBB0_1105
	v_lshlrev_b32_e32 v38, 6, v139
	v_mov_b32_e32 v39, v29
	v_lshlrev_b32_e32 v36, 6, v1
	v_mov_b32_e32 v37, v29
	s_lshl_b32 s14, s14, 2
	v_lshl_add_u64 v[38:39], s[12:13], 0, v[38:39]
	v_add_f32_e32 v33, v33, v49
	v_lshl_add_u64 v[36:37], s[12:13], 0, v[36:37]
	v_lshl_add_u64 v[38:39], v[38:39], 0, s[14:15]
	v_lshl_add_u64 v[36:37], v[36:37], 0, s[14:15]
	v_add_f32_e32 v1, v40, v41
	global_store_dword v[38:39], v33, off
	global_store_dword v[36:37], v1, off

; #define LAS __attribute__((address_space(3)))
; __device__ __forceinline__ float scan_prepare(const ScanRegs& R, const u32x2 qr_, const u32x2 qk_, const u32x2 qv_, LAS float* slot, int cq, const f32x4 mur, const f32x4 muk, const f32x4 muv, const f32x4 kkc, const f32x4 kac, const f32x4 rkc) {
;     float pr[4], pk[4], pv[4], qr[4], qk[4], qv[4], av[4], om[4];
;     unpack4(R.pr, pr); unpack4(R.pk, pk); unpack4(R.pv, pv); unpack4(qr_, qr); unpack4(qk_, qk); unpack4(qv_, qv); unpack4(R.as, av);
;     om[0] = f16_to_f((unsigned short)(R.wl.x & 0xffffu)); om[1] = f16_to_f((unsigned short)(R.wl.x >> 16)); om[2] = f16_to_f((unsigned short)(R.wl.y & 0xffffu)); om[3] = f16_to_f((unsigned short)(R.wl.y >> 16));
;     float rr[4], vv[4], kn[4], k2[4], dec[4], bu[4];
;     float ssq = 0.f, bon = 0.f, c1 = 0.f, c2 = 0.f;
; #pragma unroll
;     for (int j = 0; j < 4; ++j) {
;         rr[j] = pr[j] + (qr[j] - pr[j]) * mur[j]; const float kk0 = pk[j] + (qk[j] - pk[j]) * muk[j]; vv[j] = pv[j] + (qv[j] - pv[j]) * muv[j];
;         dec[j] = 1.0f - om[j];
;         kn[j] = kk0 * kkc[j]; ssq += kn[j] * kn[j];
;         k2[j] = kk0 * (1.0f + (av[j] - 1.0f) * kac[j]);
;         const float t = rr[j] * k2[j]; bon += t * rkc[j]; c2 += t;
;         bu[j] = kn[j] * av[j]; c1 += bu[j] * rr[j];
;     }
;     ssq += dpp_f<0x121>(ssq); bon += dpp_f<0x121>(bon); c1 += dpp_f<0x121>(c1); c2 += dpp_f<0x121>(c2);
;     ssq += dpp_f<0x122>(ssq); bon += dpp_f<0x122>(bon); c1 += dpp_f<0x122>(c1); c2 += dpp_f<0x122>(c2);
;     ssq += dpp_f<0x124>(ssq); bon += dpp_f<0x124>(bon); c1 += dpp_f<0x124>(c1); c2 += dpp_f<0x124>(c2);
;     ssq += dpp_f<0x128>(ssq); bon += dpp_f<0x128>(bon); c1 += dpp_f<0x128>(c1); c2 += dpp_f<0x128>(c2);
;     const float inv = __builtin_amdgcn_rsqf(fmaxf(ssq, 1e-24f));
;     f32x4 o_al, o_be, o_wr;
; #pragma unroll
;     for (int j = 0; j < 4; ++j) { o_al[j] = -(kn[j] * inv); o_be[j] = bu[j] * inv; o_wr[j] = dec[j] * rr[j]; }
;     LAS f32x4* s4 = (LAS f32x4*)slot;
;     s4[cq] = (f32x4){dec[0], dec[1], dec[2], dec[3]}; s4[16 + cq] = (f32x4){k2[0], k2[1], k2[2], k2[3]}; s4[32 + cq] = o_al; s4[48 + cq] = o_be; s4[64 + cq] = o_wr;
;     s4[80 + cq] = (f32x4){vv[0], vv[1], vv[2], vv[3]};
;     if (cq == 0) *(LAS f32x2*)(slot + 384) = (f32x2){c1 * inv, c2};
;     return bon;
; }
.LBB0_1109:
	s_waitcnt vmcnt(8)
	v_lshlrev_b32_e32 v108, 16, v46
	v_and_b32_e32 v109, 0xffff0000, v46
	v_lshlrev_b32_e32 v110, 16, v38
	v_and_b32_e32 v111, 0xffff0000, v38
	v_pk_add_f32 v[110:111], v[110:111], v[108:109] neg_lo:[0,1] neg_hi:[0,1]
	v_lshlrev_b32_e32 v140, 16, v39
	v_pk_fma_f32 v[144:145], v[6:7], v[110:111], v[108:109]
	v_lshlrev_b32_e32 v110, 16, v47
	v_and_b32_e32 v111, 0xffff0000, v47
	v_and_b32_e32 v141, 0xffff0000, v39
	v_pk_add_f32 v[140:141], v[140:141], v[110:111] neg_lo:[0,1] neg_hi:[0,1]
	v_lshlrev_b32_e32 v118, 16, v40
	v_and_b32_e32 v119, 0xffff0000, v40
	v_pk_fma_f32 v[146:147], v[8:9], v[140:141], v[110:111]
	v_lshlrev_b32_e32 v140, 16, v34
	v_and_b32_e32 v141, 0xffff0000, v34
	s_waitcnt vmcnt(3)
	v_lshlrev_b32_e32 v142, 16, v48
	v_and_b32_e32 v143, 0xffff0000, v48
	v_pk_add_f32 v[140:141], v[140:141], v[118:119] neg_lo:[0,1] neg_hi:[0,1]
	v_pk_add_f32 v[148:149], v[142:143], -1.0 op_sel_hi:[1,0]
	v_pk_fma_f32 v[140:141], v[2:3], v[140:141], v[118:119]
	v_pk_fma_f32 v[148:149], v[18:19], v[148:149], 1.0 op_sel_hi:[1,1,0]
	v_pk_mul_f32 v[154:155], v[14:15], v[140:141]
	v_pk_mul_f32 v[148:149], v[148:149], v[140:141]
	v_cvt_f32_f16_sdwa v141, v44 dst_sel:DWORD dst_unused:UNUSED_PAD src0_sel:WORD_1
	v_cvt_f32_f16_e32 v140, v44
	v_lshlrev_b32_e32 v114, 16, v36
	v_and_b32_e32 v115, 0xffff0000, v36
	v_lshlrev_b32_e32 v156, 16, v42
	v_and_b32_e32 v157, 0xffff0000, v42
	v_pk_add_f32 v[152:153], v[140:141], 1.0 op_sel_hi:[1,0] neg_lo:[1,0] neg_hi:[1,0]
	v_pk_add_f32 v[140:141], v[156:157], v[114:115] neg_lo:[0,1] neg_hi:[0,1]
	v_lshlrev_b32_e32 v116, 16, v41
	v_pk_fma_f32 v[164:165], v[10:11], v[140:141], v[114:115]
	v_and_b32_e32 v117, 0xffff0000, v41
	v_pk_mul_f32 v[140:141], v[164:165], v[148:149]
	v_pk_mul_f32 v[150:151], v[154:155], v[154:155]
	v_fma_f32 v33, v22, v140, 0
	v_fmac_f32_e32 v33, v23, v141
	v_lshlrev_b32_e32 v140, 16, v35
	v_and_b32_e32 v141, 0xffff0000, v35
	v_pk_add_f32 v[140:141], v[140:141], v[116:117] neg_lo:[0,1] neg_hi:[0,1]
	v_add_f32_e32 v28, v150, v151
	v_pk_fma_f32 v[140:141], v[4:5], v[140:141], v[116:117]
	v_pk_mul_f32 v[142:143], v[154:155], v[142:143]
	v_pk_mul_f32 v[158:159], v[16:17], v[140:141]
	v_pk_mul_f32 v[160:161], v[158:159], v[158:159]
	v_add_f32_e32 v28, v160, v28
	v_add_f32_e32 v28, v161, v28
	v_lshlrev_b32_e32 v156, 16, v49
	s_nop 0
	v_add_f32_dpp v28, v28, v28 row_ror:1 row_mask:0xf bank_mask:0xf bound_ctrl:1
	v_and_b32_e32 v157, 0xffff0000, v49
	v_lshlrev_b32_e32 v112, 16, v37
	v_add_f32_dpp v28, v28, v28 row_ror:2 row_mask:0xf bank_mask:0xf bound_ctrl:1
	v_and_b32_e32 v113, 0xffff0000, v37
	v_pk_add_f32 v[162:163], v[156:157], -1.0 op_sel_hi:[1,0]
	v_add_f32_dpp v28, v28, v28 row_ror:4 row_mask:0xf bank_mask:0xf bound_ctrl:1
	v_pk_fma_f32 v[150:151], v[20:21], v[162:163], 1.0 op_sel_hi:[1,1,0]
	v_pk_mul_f32 v[164:165], v[164:165], 1.0 op_sel_hi:[1,0]
	v_add_f32_dpp v28, v28, v28 row_ror:8 row_mask:0xf bank_mask:0xf bound_ctrl:1
	v_max_f32_e32 v28, 0x179abe15, v28
	v_rsq_f32_e32 v28, v28
	v_pk_mul_f32 v[150:151], v[150:151], v[140:141]
	v_pk_mul_f32 v[140:141], v[158:159], v[156:157]
	v_pk_mul_f32 v[160:161], v[142:143], v[28:29] op_sel_hi:[1,0]
	v_lshlrev_b32_e32 v142, 16, v43
	v_and_b32_e32 v143, 0xffff0000, v43
	v_pk_add_f32 v[142:143], v[142:143], v[112:113] neg_lo:[0,1] neg_hi:[0,1]
	v_pk_mul_f32 v[162:163], v[140:141], v[28:29] op_sel_hi:[1,0]
	v_pk_fma_f32 v[166:167], v[12:13], v[142:143], v[112:113]
	v_pk_mul_f32 v[156:157], v[154:155], v[28:29] op_sel_hi:[1,0] neg_lo:[0,1] neg_hi:[0,1]
	v_pk_mul_f32 v[142:143], v[166:167], v[150:151]
	v_fmac_f32_e32 v33, v24, v142
	v_cvt_f32_f16_sdwa v155, v45 dst_sel:DWORD dst_unused:UNUSED_PAD src0_sel:WORD_1
	v_cvt_f32_f16_e32 v154, v45
	v_fmac_f32_e32 v33, v25, v143
	s_nop 1
	v_add_f32_dpp v33, v33, v33 row_ror:1 row_mask:0xf bank_mask:0xf bound_ctrl:1
	s_nop 1
	v_add_f32_dpp v33, v33, v33 row_ror:2 row_mask:0xf bank_mask:0xf bound_ctrl:1
	s_nop 1
	v_add_f32_dpp v33, v33, v33 row_ror:4 row_mask:0xf bank_mask:0xf bound_ctrl:1
	v_mov_b32_e32 v81, 0
	v_pk_add_f32 v[154:155], v[154:155], 1.0 op_sel_hi:[1,0] neg_lo:[1,0] neg_hi:[1,0]
	s_nop 0
	v_mov_b32_dpp v81, v33 row_ror:8 row_mask:0xf bank_mask:0xf
	v_pk_mul_f32 v[158:159], v[158:159], v[28:29] op_sel_hi:[1,0] neg_lo:[0,1] neg_hi:[0,1]
	v_pk_mul_f32 v[166:167], v[166:167], 1.0 op_sel_hi:[1,0]
	ds_write_b128 v127, v[152:155] offset:50176
	ds_write_b128 v127, v[148:151] offset:50432
	ds_write_b128 v127, v[156:159] offset:50688
	ds_write_b128 v127, v[160:163] offset:50944
	ds_write_b128 v127, v[164:167] offset:51200
	ds_write_b128 v127, v[144:147] offset:51456
	s_and_saveexec_b64 s[52:53], s[4:5]
	s_or_b64 exec, exec, s[52:53]
	s_waitcnt vmcnt(17)
; #define LAS __attribute__((address_space(3)))
; __device__ __forceinline__ float scan_prepare(const ScanRegs& R, const u32x2 qr_, const u32x2 qk_, const u32x2 qv_, LAS float* slot, int cq, const f32x4 mur, const f32x4 muk, const f32x4 muv, const f32x4 kkc, const f32x4 kac, const f32x4 rkc) {
;     float pr[4], pk[4], pv[4], qr[4], qk[4], qv[4], av[4], om[4];
;     unpack4(R.pr, pr); unpack4(R.pk, pk); unpack4(R.pv, pv); unpack4(qr_, qr); unpack4(qk_, qk); unpack4(qv_, qv); unpack4(R.as, av);
;     om[0] = f16_to_f((unsigned short)(R.wl.x & 0xffffu)); om[1] = f16_to_f((unsigned short)(R.wl.x >> 16)); om[2] = f16_to_f((unsigned short)(R.wl.y & 0xffffu)); om[3] = f16_to_f((unsigned short)(R.wl.y >> 16));
;     float rr[4], vv[4], kn[4], k2[4], dec[4], bu[4];
;     float ssq = 0.f, bon = 0.f, c1 = 0.f, c2 = 0.f;
; #pragma unroll
;     for (int j = 0; j < 4; ++j) {
;         rr[j] = pr[j] + (qr[j] - pr[j]) * mur[j]; const float kk0 = pk[j] + (qk[j] - pk[j]) * muk[j]; vv[j] = pv[j] + (qv[j] - pv[j]) * muv[j];
;         dec[j] = 1.0f - om[j];
;         kn[j] = kk0 * kkc[j]; ssq += kn[j] * kn[j];
;         k2[j] = kk0 * (1.0f + (av[j] - 1.0f) * kac[j]);
;         const float t = rr[j] * k2[j]; bon += t * rkc[j]; c2 += t;
;         bu[j] = kn[j] * av[j]; c1 += bu[j] * rr[j];
;     }
;     ssq += dpp_f<0x121>(ssq); bon += dpp_f<0x121>(bon); c1 += dpp_f<0x121>(c1); c2 += dpp_f<0x121>(c2);
;     ssq += dpp_f<0x122>(ssq); bon += dpp_f<0x122>(bon); c1 += dpp_f<0x122>(c1); c2 += dpp_f<0x122>(c2);
;     ssq += dpp_f<0x124>(ssq); bon += dpp_f<0x124>(bon); c1 += dpp_f<0x124>(c1); c2 += dpp_f<0x124>(c2);
;     ssq += dpp_f<0x128>(ssq); bon += dpp_f<0x128>(bon); c1 += dpp_f<0x128>(c1); c2 += dpp_f<0x128>(c2);
;     const float inv = __builtin_amdgcn_rsqf(fmaxf(ssq, 1e-24f));
;     f32x4 o_al, o_be, o_wr;
; #pragma unroll
;     for (int j = 0; j < 4; ++j) { o_al[j] = -(kn[j] * inv); o_be[j] = bu[j] * inv; o_wr[j] = dec[j] * rr[j]; }
;     LAS f32x4* s4 = (LAS f32x4*)slot;
;     s4[cq] = (f32x4){dec[0], dec[1], dec[2], dec[3]}; s4[16 + cq] = (f32x4){k2[0], k2[1], k2[2], k2[3]}; s4[32 + cq] = o_al; s4[48 + cq] = o_be; s4[64 + cq] = o_wr;
;     s4[80 + cq] = (f32x4){vv[0], vv[1], vv[2], vv[3]};
;     if (cq == 0) *(LAS f32x2*)(slot + 384) = (f32x2){c1 * inv, c2};
;     return bon;
; }
	v_lshlrev_b32_e32 v140, 16, v50
	v_and_b32_e32 v141, 0xffff0000, v50
	s_waitcnt vmcnt(2)
	v_lshlrev_b32_e32 v142, 16, v58
	v_and_b32_e32 v143, 0xffff0000, v58
	v_pk_add_f32 v[118:119], v[118:119], v[140:141] neg_lo:[0,1] neg_hi:[0,1]
	v_lshlrev_b32_e32 v150, 16, v59
	v_pk_fma_f32 v[118:119], v[2:3], v[118:119], v[140:141]
	v_pk_add_f32 v[140:141], v[142:143], -1.0 op_sel_hi:[1,0]
	v_pk_mul_f32 v[146:147], v[14:15], v[118:119]
	v_pk_fma_f32 v[140:141], v[18:19], v[140:141], 1.0 op_sel_hi:[1,1,0]
	v_pk_mul_f32 v[152:153], v[146:147], v[142:143]
	v_pk_mul_f32 v[140:141], v[140:141], v[118:119]
	v_cvt_f32_f16_sdwa v119, v52 dst_sel:DWORD dst_unused:UNUSED_PAD src0_sel:WORD_1
	v_cvt_f32_f16_e32 v118, v52
	s_waitcnt vmcnt(6)
	v_lshlrev_b32_e32 v142, 16, v82
	v_and_b32_e32 v143, 0xffff0000, v82
	v_pk_add_f32 v[114:115], v[114:115], v[142:143] neg_lo:[0,1] neg_hi:[0,1]
	v_pk_add_f32 v[144:145], v[118:119], 1.0 op_sel_hi:[1,0] neg_lo:[1,0] neg_hi:[1,0]
	v_pk_fma_f32 v[118:119], v[10:11], v[114:115], v[142:143]
	v_pk_mul_f32 v[148:149], v[146:147], v[146:147]
	v_pk_mul_f32 v[114:115], v[118:119], v[140:141]
	v_fma_f32 v156, v22, v114, 0
	v_fmac_f32_e32 v156, v23, v115
	v_lshlrev_b32_e32 v114, 16, v51
	v_and_b32_e32 v115, 0xffff0000, v51
	v_pk_add_f32 v[116:117], v[116:117], v[114:115] neg_lo:[0,1] neg_hi:[0,1]
	v_add_f32_e32 v28, v148, v149
	v_pk_fma_f32 v[114:115], v[4:5], v[116:117], v[114:115]
	v_and_b32_e32 v151, 0xffff0000, v59
	v_pk_mul_f32 v[116:117], v[16:17], v[114:115]
	v_pk_add_f32 v[154:155], v[150:151], -1.0 op_sel_hi:[1,0]
	v_pk_mul_f32 v[142:143], v[116:117], v[116:117]
	s_waitcnt vmcnt(5)
	v_lshlrev_b32_e32 v160, 16, v88
	v_add_f32_e32 v28, v142, v28
	v_add_f32_e32 v28, v143, v28
	v_pk_fma_f32 v[142:143], v[20:21], v[154:155], 1.0 op_sel_hi:[1,1,0]
	v_and_b32_e32 v161, 0xffff0000, v88
	v_add_f32_dpp v28, v28, v28 row_ror:1 row_mask:0xf bank_mask:0xf bound_ctrl:1
	v_pk_mul_f32 v[142:143], v[142:143], v[114:115]
	v_pk_mul_f32 v[114:115], v[116:117], v[150:151]
	v_add_f32_dpp v28, v28, v28 row_ror:2 row_mask:0xf bank_mask:0xf bound_ctrl:1
	v_lshlrev_b32_e32 v162, 16, v89
	v_and_b32_e32 v163, 0xffff0000, v89
	v_add_f32_dpp v28, v28, v28 row_ror:4 row_mask:0xf bank_mask:0xf bound_ctrl:1
	v_pk_add_f32 v[108:109], v[108:109], v[160:161] neg_lo:[0,1] neg_hi:[0,1]
	v_pk_add_f32 v[110:111], v[110:111], v[162:163] neg_lo:[0,1] neg_hi:[0,1]
	v_add_f32_dpp v28, v28, v28 row_ror:8 row_mask:0xf bank_mask:0xf bound_ctrl:1
	v_max_f32_e32 v28, 0x179abe15, v28
	v_rsq_f32_e32 v28, v28
	v_pk_fma_f32 v[110:111], v[8:9], v[110:111], v[162:163]
	v_pk_fma_f32 v[108:109], v[6:7], v[108:109], v[160:161]
	v_pk_mul_f32 v[150:151], v[116:117], v[28:29] op_sel_hi:[1,0] neg_lo:[0,1] neg_hi:[0,1]
	v_lshlrev_b32_e32 v116, 16, v83
	v_and_b32_e32 v117, 0xffff0000, v83
	v_pk_add_f32 v[112:113], v[112:113], v[116:117] neg_lo:[0,1] neg_hi:[0,1]
	v_pk_mul_f32 v[154:155], v[114:115], v[28:29] op_sel_hi:[1,0]
	v_pk_fma_f32 v[158:159], v[12:13], v[112:113], v[116:117]
	v_pk_mul_f32 v[148:149], v[146:147], v[28:29] op_sel_hi:[1,0] neg_lo:[0,1] neg_hi:[0,1]
	v_pk_mul_f32 v[112:113], v[158:159], v[142:143]
	v_fmac_f32_e32 v156, v24, v112
	v_cvt_f32_f16_sdwa v147, v53 dst_sel:DWORD dst_unused:UNUSED_PAD src0_sel:WORD_1
	v_cvt_f32_f16_e32 v146, v53
	v_fmac_f32_e32 v156, v25, v113
	s_nop 1
	v_add_f32_dpp v114, v156, v156 row_ror:1 row_mask:0xf bank_mask:0xf bound_ctrl:1
	s_nop 1
	v_add_f32_dpp v114, v114, v114 row_ror:2 row_mask:0xf bank_mask:0xf bound_ctrl:1
	s_nop 1
	v_add_f32_dpp v112, v114, v114 row_ror:4 row_mask:0xf bank_mask:0xf bound_ctrl:1
	v_mov_b32_e32 v113, 0
	v_pk_add_f32 v[146:147], v[146:147], 1.0 op_sel_hi:[1,0] neg_lo:[1,0] neg_hi:[1,0]
	s_nop 0
	v_mov_b32_dpp v113, v112 row_ror:8 row_mask:0xf bank_mask:0xf
	v_pk_mul_f32 v[152:153], v[152:153], v[28:29] op_sel_hi:[1,0]
	v_pk_mul_f32 v[156:157], v[118:119], 1.0 op_sel_hi:[1,0]
	v_pk_mul_f32 v[158:159], v[158:159], 1.0 op_sel_hi:[1,0]
	ds_write_b128 v129, v[144:147] offset:50176
	ds_write_b128 v129, v[140:143] offset:50432
	ds_write_b128 v129, v[148:151] offset:50688
	ds_write_b128 v129, v[152:155] offset:50944
	ds_write_b128 v129, v[156:159] offset:51200
	ds_write_b128 v129, v[108:111] offset:51456
	s_and_saveexec_b64 s[52:53], s[4:5]
	s_cbranch_execz .LBB0_1121
	s_or_b64 exec, exec, s[52:53]
	s_and_saveexec_b64 s[52:53], s[44:45]
	s_cbranch_execnz .LBB0_1122

; #define LAS __attribute__((address_space(3)))
; __device__ __forceinline__ float scan_prepare(const ScanRegs& R, const u32x2 qr_, const u32x2 qk_, const u32x2 qv_, LAS float* slot, int cq, const f32x4 mur, const f32x4 muk, const f32x4 muv, const f32x4 kkc, const f32x4 kac, const f32x4 rkc) {
;     float pr[4], pk[4], pv[4], qr[4], qk[4], qv[4], av[4], om[4];
;     unpack4(R.pr, pr); unpack4(R.pk, pk); unpack4(R.pv, pv); unpack4(qr_, qr); unpack4(qk_, qk); unpack4(qv_, qv); unpack4(R.as, av);
;     om[0] = f16_to_f((unsigned short)(R.wl.x & 0xffffu)); om[1] = f16_to_f((unsigned short)(R.wl.x >> 16)); om[2] = f16_to_f((unsigned short)(R.wl.y & 0xffffu)); om[3] = f16_to_f((unsigned short)(R.wl.y >> 16));
;     float rr[4], vv[4], kn[4], k2[4], dec[4], bu[4];
;     float ssq = 0.f, bon = 0.f, c1 = 0.f, c2 = 0.f;
; #pragma unroll
;     for (int j = 0; j < 4; ++j) {
;         rr[j] = pr[j] + (qr[j] - pr[j]) * mur[j]; const float kk0 = pk[j] + (qk[j] - pk[j]) * muk[j]; vv[j] = pv[j] + (qv[j] - pv[j]) * muv[j];
;         dec[j] = 1.0f - om[j];
;         kn[j] = kk0 * kkc[j]; ssq += kn[j] * kn[j];
;         k2[j] = kk0 * (1.0f + (av[j] - 1.0f) * kac[j]);
;         const float t = rr[j] * k2[j]; bon += t * rkc[j]; c2 += t;
;         bu[j] = kn[j] * av[j]; c1 += bu[j] * rr[j];
;     }
;     ssq += dpp_f<0x121>(ssq); bon += dpp_f<0x121>(bon); c1 += dpp_f<0x121>(c1); c2 += dpp_f<0x121>(c2);
;     ssq += dpp_f<0x122>(ssq); bon += dpp_f<0x122>(bon); c1 += dpp_f<0x122>(c1); c2 += dpp_f<0x122>(c2);
;     ssq += dpp_f<0x124>(ssq); bon += dpp_f<0x124>(bon); c1 += dpp_f<0x124>(c1); c2 += dpp_f<0x124>(c2);
;     ssq += dpp_f<0x128>(ssq); bon += dpp_f<0x128>(bon); c1 += dpp_f<0x128>(c1); c2 += dpp_f<0x128>(c2);
;     const float inv = __builtin_amdgcn_rsqf(fmaxf(ssq, 1e-24f));
;     f32x4 o_al, o_be, o_wr;
; #pragma unroll
;     for (int j = 0; j < 4; ++j) { o_al[j] = -(kn[j] * inv); o_be[j] = bu[j] * inv; o_wr[j] = dec[j] * rr[j]; }
;     LAS f32x4* s4 = (LAS f32x4*)slot;
;     s4[cq] = (f32x4){dec[0], dec[1], dec[2], dec[3]}; s4[16 + cq] = (f32x4){k2[0], k2[1], k2[2], k2[3]}; s4[32 + cq] = o_al; s4[48 + cq] = o_be; s4[64 + cq] = o_wr;
;     s4[80 + cq] = (f32x4){vv[0], vv[1], vv[2], vv[3]};
;     if (cq == 0) *(LAS f32x2*)(slot + 384) = (f32x2){c1 * inv, c2};
;     return bon;
; }
.LBB0_1115:
	v_add_u32_e32 v28, v120, v130
	s_waitcnt lgkmcnt(0)
	s_barrier
	ds_read_b128 v[108:111], v28
	v_lshl_add_u64 v[112:113], s[92:93], 0, v[100:101]
	v_add_co_u32_e32 v112, vcc, s68, v112
	s_cmpk_gt_u32 s14, 0xfd
	s_waitcnt lgkmcnt(0)
	v_add_f32_e32 v28, v108, v109
	v_add_f32_e32 v33, v110, v111
	v_add_f32_e32 v28, v28, v33
	v_bfe_u32 v33, v28, 16, 1
	v_add3_u32 v28, v28, v33, s67
	v_addc_co_u32_e32 v113, vcc, 0, v113, vcc
	global_store_short_d16_hi v[112:113], v28, off
	v_add_u32_e32 v28, v120, v131
	ds_read_b128 v[108:111], v28
	s_cselect_b64 s[52:53], -1, 0
	s_and_b64 vcc, exec, s[52:53]
	s_waitcnt lgkmcnt(0)
	v_add_f32_e32 v28, v108, v109
	v_add_f32_e32 v33, v110, v111
	v_add_f32_e32 v28, v28, v33
	v_bfe_u32 v33, v28, 16, 1
	v_add3_u32 v28, v28, v33, s67
	global_store_short_d16_hi v[112:113], v28, off offset:2048
	s_cbranch_vccnz .LBB0_1106
	v_lshlrev_b32_e32 v108, 16, v76
	v_and_b32_e32 v109, 0xffff0000, v76
	v_lshlrev_b32_e32 v110, 16, v62
	v_and_b32_e32 v111, 0xffff0000, v62
	v_pk_add_f32 v[110:111], v[110:111], v[108:109] neg_lo:[0,1] neg_hi:[0,1]
	v_lshlrev_b32_e32 v140, 16, v63
	v_pk_fma_f32 v[144:145], v[6:7], v[110:111], v[108:109]
	v_lshlrev_b32_e32 v110, 16, v77
	v_and_b32_e32 v111, 0xffff0000, v77
	v_and_b32_e32 v141, 0xffff0000, v63
	v_pk_add_f32 v[140:141], v[140:141], v[110:111] neg_lo:[0,1] neg_hi:[0,1]
	v_lshlrev_b32_e32 v118, 16, v64
	v_and_b32_e32 v119, 0xffff0000, v64
	v_pk_fma_f32 v[146:147], v[8:9], v[140:141], v[110:111]
	v_lshlrev_b32_e32 v140, 16, v54
	v_and_b32_e32 v141, 0xffff0000, v54
	s_waitcnt vmcnt(3)
	v_lshlrev_b32_e32 v142, 16, v86
	v_and_b32_e32 v143, 0xffff0000, v86
	v_pk_add_f32 v[140:141], v[140:141], v[118:119] neg_lo:[0,1] neg_hi:[0,1]
	v_pk_add_f32 v[148:149], v[142:143], -1.0 op_sel_hi:[1,0]
	v_pk_fma_f32 v[140:141], v[2:3], v[140:141], v[118:119]
	v_pk_fma_f32 v[148:149], v[18:19], v[148:149], 1.0 op_sel_hi:[1,1,0]
	v_pk_mul_f32 v[154:155], v[14:15], v[140:141]
	v_pk_mul_f32 v[148:149], v[140:141], v[148:149]
	v_cvt_f32_f16_sdwa v141, v72 dst_sel:DWORD dst_unused:UNUSED_PAD src0_sel:WORD_1
	v_cvt_f32_f16_e32 v140, v72
	v_lshlrev_b32_e32 v114, 16, v56
	v_and_b32_e32 v115, 0xffff0000, v56
	v_lshlrev_b32_e32 v156, 16, v68
	v_and_b32_e32 v157, 0xffff0000, v68
	v_pk_add_f32 v[152:153], v[140:141], 1.0 op_sel_hi:[1,0] neg_lo:[1,0] neg_hi:[1,0]
	v_pk_add_f32 v[140:141], v[156:157], v[114:115] neg_lo:[0,1] neg_hi:[0,1]
	v_lshlrev_b32_e32 v116, 16, v65
	v_pk_fma_f32 v[164:165], v[10:11], v[140:141], v[114:115]
	v_and_b32_e32 v117, 0xffff0000, v65
	v_pk_mul_f32 v[140:141], v[164:165], v[148:149]
	v_pk_mul_f32 v[150:151], v[154:155], v[154:155]
	v_fma_f32 v33, v22, v140, 0
	v_fmac_f32_e32 v33, v23, v141
	v_lshlrev_b32_e32 v140, 16, v55
	v_and_b32_e32 v141, 0xffff0000, v55
	v_pk_add_f32 v[140:141], v[140:141], v[116:117] neg_lo:[0,1] neg_hi:[0,1]
	v_add_f32_e32 v28, v150, v151
	v_pk_fma_f32 v[140:141], v[4:5], v[140:141], v[116:117]
	v_pk_mul_f32 v[142:143], v[154:155], v[142:143]
	v_pk_mul_f32 v[158:159], v[16:17], v[140:141]
	v_pk_mul_f32 v[160:161], v[158:159], v[158:159]
	v_add_f32_e32 v28, v160, v28
	v_add_f32_e32 v28, v161, v28
	v_lshlrev_b32_e32 v156, 16, v87
	s_nop 0
	v_add_f32_dpp v28, v28, v28 row_ror:1 row_mask:0xf bank_mask:0xf bound_ctrl:1
	v_and_b32_e32 v157, 0xffff0000, v87
	v_lshlrev_b32_e32 v112, 16, v57
	v_add_f32_dpp v28, v28, v28 row_ror:2 row_mask:0xf bank_mask:0xf bound_ctrl:1
	v_and_b32_e32 v113, 0xffff0000, v57
	v_pk_add_f32 v[162:163], v[156:157], -1.0 op_sel_hi:[1,0]
	v_add_f32_dpp v28, v28, v28 row_ror:4 row_mask:0xf bank_mask:0xf bound_ctrl:1
	v_pk_fma_f32 v[150:151], v[20:21], v[162:163], 1.0 op_sel_hi:[1,1,0]
	v_pk_mul_f32 v[164:165], v[164:165], 1.0 op_sel_hi:[1,0]
	v_add_f32_dpp v28, v28, v28 row_ror:8 row_mask:0xf bank_mask:0xf bound_ctrl:1
	v_max_f32_e32 v28, 0x179abe15, v28
	v_rsq_f32_e32 v28, v28
	v_pk_mul_f32 v[150:151], v[140:141], v[150:151]
	v_pk_mul_f32 v[140:141], v[158:159], v[156:157]
	v_pk_mul_f32 v[160:161], v[142:143], v[28:29] op_sel_hi:[1,0]
	v_lshlrev_b32_e32 v142, 16, v69
	v_and_b32_e32 v143, 0xffff0000, v69
	v_pk_add_f32 v[142:143], v[142:143], v[112:113] neg_lo:[0,1] neg_hi:[0,1]
	v_pk_mul_f32 v[162:163], v[140:141], v[28:29] op_sel_hi:[1,0]
	v_pk_fma_f32 v[166:167], v[12:13], v[142:143], v[112:113]
	v_pk_mul_f32 v[156:157], v[154:155], v[28:29] op_sel_hi:[1,0] neg_lo:[0,1] neg_hi:[0,1]
	v_pk_mul_f32 v[142:143], v[166:167], v[150:151]
	v_fmac_f32_e32 v33, v24, v142
	v_cvt_f32_f16_sdwa v155, v73 dst_sel:DWORD dst_unused:UNUSED_PAD src0_sel:WORD_1
	v_cvt_f32_f16_e32 v154, v73
	v_fmac_f32_e32 v33, v25, v143
	s_nop 1
	v_add_f32_dpp v33, v33, v33 row_ror:1 row_mask:0xf bank_mask:0xf bound_ctrl:1
	s_nop 1
	v_add_f32_dpp v33, v33, v33 row_ror:2 row_mask:0xf bank_mask:0xf bound_ctrl:1
	s_nop 1
	v_add_f32_dpp v33, v33, v33 row_ror:4 row_mask:0xf bank_mask:0xf bound_ctrl:1
	v_mov_b32_e32 v81, 0
	v_pk_add_f32 v[154:155], v[154:155], 1.0 op_sel_hi:[1,0] neg_lo:[1,0] neg_hi:[1,0]
	s_nop 0
	v_mov_b32_dpp v81, v33 row_ror:8 row_mask:0xf bank_mask:0xf
	v_pk_mul_f32 v[158:159], v[158:159], v[28:29] op_sel_hi:[1,0] neg_lo:[0,1] neg_hi:[0,1]
	v_pk_mul_f32 v[166:167], v[166:167], 1.0 op_sel_hi:[1,0]
	ds_write_b128 v127, v[152:155]
	ds_write_b128 v127, v[148:151] offset:256
	ds_write_b128 v127, v[156:159] offset:512
	ds_write_b128 v127, v[160:163] offset:768
	ds_write_b128 v127, v[164:167] offset:1024
	ds_write_b128 v127, v[144:147] offset:1280
	s_and_saveexec_b64 s[56:57], s[4:5]
	s_or_b64 exec, exec, s[56:57]
	s_waitcnt vmcnt(4)
; #define LAS __attribute__((address_space(3)))
; __device__ __forceinline__ float scan_prepare(const ScanRegs& R, const u32x2 qr_, const u32x2 qk_, const u32x2 qv_, LAS float* slot, int cq, const f32x4 mur, const f32x4 muk, const f32x4 muv, const f32x4 kkc, const f32x4 kac, const f32x4 rkc) {
;     float pr[4], pk[4], pv[4], qr[4], qk[4], qv[4], av[4], om[4];
;     unpack4(R.pr, pr); unpack4(R.pk, pk); unpack4(R.pv, pv); unpack4(qr_, qr); unpack4(qk_, qk); unpack4(qv_, qv); unpack4(R.as, av);
;     om[0] = f16_to_f((unsigned short)(R.wl.x & 0xffffu)); om[1] = f16_to_f((unsigned short)(R.wl.x >> 16)); om[2] = f16_to_f((unsigned short)(R.wl.y & 0xffffu)); om[3] = f16_to_f((unsigned short)(R.wl.y >> 16));
;     float rr[4], vv[4], kn[4], k2[4], dec[4], bu[4];
;     float ssq = 0.f, bon = 0.f, c1 = 0.f, c2 = 0.f;
; #pragma unroll
;     for (int j = 0; j < 4; ++j) {
;         rr[j] = pr[j] + (qr[j] - pr[j]) * mur[j]; const float kk0 = pk[j] + (qk[j] - pk[j]) * muk[j]; vv[j] = pv[j] + (qv[j] - pv[j]) * muv[j];
;         dec[j] = 1.0f - om[j];
;         kn[j] = kk0 * kkc[j]; ssq += kn[j] * kn[j];
;         k2[j] = kk0 * (1.0f + (av[j] - 1.0f) * kac[j]);
;         const float t = rr[j] * k2[j]; bon += t * rkc[j]; c2 += t;
;         bu[j] = kn[j] * av[j]; c1 += bu[j] * rr[j];
;     }
;     ssq += dpp_f<0x121>(ssq); bon += dpp_f<0x121>(bon); c1 += dpp_f<0x121>(c1); c2 += dpp_f<0x121>(c2);
;     ssq += dpp_f<0x122>(ssq); bon += dpp_f<0x122>(bon); c1 += dpp_f<0x122>(c1); c2 += dpp_f<0x122>(c2);
;     ssq += dpp_f<0x124>(ssq); bon += dpp_f<0x124>(bon); c1 += dpp_f<0x124>(c1); c2 += dpp_f<0x124>(c2);
;     ssq += dpp_f<0x128>(ssq); bon += dpp_f<0x128>(bon); c1 += dpp_f<0x128>(c1); c2 += dpp_f<0x128>(c2);
;     const float inv = __builtin_amdgcn_rsqf(fmaxf(ssq, 1e-24f));
;     f32x4 o_al, o_be, o_wr;
; #pragma unroll
;     for (int j = 0; j < 4; ++j) { o_al[j] = -(kn[j] * inv); o_be[j] = bu[j] * inv; o_wr[j] = dec[j] * rr[j]; }
;     LAS f32x4* s4 = (LAS f32x4*)slot;
;     s4[cq] = (f32x4){dec[0], dec[1], dec[2], dec[3]}; s4[16 + cq] = (f32x4){k2[0], k2[1], k2[2], k2[3]}; s4[32 + cq] = o_al; s4[48 + cq] = o_be; s4[64 + cq] = o_wr;
;     s4[80 + cq] = (f32x4){vv[0], vv[1], vv[2], vv[3]};
;     if (cq == 0) *(LAS f32x2*)(slot + 384) = (f32x2){c1 * inv, c2};
;     return bon;
; }
	v_lshlrev_b32_e32 v140, 16, v96
	v_and_b32_e32 v141, 0xffff0000, v96
	s_waitcnt vmcnt(2)
	v_lshlrev_b32_e32 v142, 16, v102
	v_and_b32_e32 v143, 0xffff0000, v102
	v_pk_add_f32 v[118:119], v[118:119], v[140:141] neg_lo:[0,1] neg_hi:[0,1]
	v_lshlrev_b32_e32 v150, 16, v103
	v_pk_fma_f32 v[118:119], v[2:3], v[118:119], v[140:141]
	v_pk_add_f32 v[140:141], v[142:143], -1.0 op_sel_hi:[1,0]
	v_pk_mul_f32 v[146:147], v[14:15], v[118:119]
	v_pk_fma_f32 v[140:141], v[18:19], v[140:141], 1.0 op_sel_hi:[1,1,0]
	v_pk_mul_f32 v[152:153], v[146:147], v[142:143]
	v_pk_mul_f32 v[140:141], v[140:141], v[118:119]
	v_cvt_f32_f16_sdwa v119, v98 dst_sel:DWORD dst_unused:UNUSED_PAD src0_sel:WORD_1
	v_cvt_f32_f16_e32 v118, v98
	v_lshlrev_b32_e32 v142, 16, v84
	v_and_b32_e32 v143, 0xffff0000, v84
	v_pk_add_f32 v[114:115], v[114:115], v[142:143] neg_lo:[0,1] neg_hi:[0,1]
	v_pk_add_f32 v[144:145], v[118:119], 1.0 op_sel_hi:[1,0] neg_lo:[1,0] neg_hi:[1,0]
	v_pk_fma_f32 v[118:119], v[10:11], v[114:115], v[142:143]
	v_pk_mul_f32 v[148:149], v[146:147], v[146:147]
	v_pk_mul_f32 v[114:115], v[118:119], v[140:141]
	v_fma_f32 v156, v22, v114, 0
	v_fmac_f32_e32 v156, v23, v115
	v_lshlrev_b32_e32 v114, 16, v97
	v_and_b32_e32 v115, 0xffff0000, v97
	v_pk_add_f32 v[116:117], v[116:117], v[114:115] neg_lo:[0,1] neg_hi:[0,1]
	v_add_f32_e32 v28, v148, v149
	v_pk_fma_f32 v[114:115], v[4:5], v[116:117], v[114:115]
	v_and_b32_e32 v151, 0xffff0000, v103
	v_pk_mul_f32 v[116:117], v[16:17], v[114:115]
	v_pk_add_f32 v[154:155], v[150:151], -1.0 op_sel_hi:[1,0]
	v_pk_mul_f32 v[142:143], v[116:117], v[116:117]
	v_lshlrev_b32_e32 v160, 16, v94
	v_add_f32_e32 v28, v142, v28
	v_add_f32_e32 v28, v143, v28
	v_pk_fma_f32 v[142:143], v[20:21], v[154:155], 1.0 op_sel_hi:[1,1,0]
	v_and_b32_e32 v161, 0xffff0000, v94
	v_add_f32_dpp v28, v28, v28 row_ror:1 row_mask:0xf bank_mask:0xf bound_ctrl:1
	v_pk_mul_f32 v[142:143], v[142:143], v[114:115]
	v_pk_mul_f32 v[114:115], v[116:117], v[150:151]
	v_add_f32_dpp v28, v28, v28 row_ror:2 row_mask:0xf bank_mask:0xf bound_ctrl:1
	v_lshlrev_b32_e32 v162, 16, v95
	v_and_b32_e32 v163, 0xffff0000, v95
	v_add_f32_dpp v28, v28, v28 row_ror:4 row_mask:0xf bank_mask:0xf bound_ctrl:1
	v_pk_add_f32 v[108:109], v[108:109], v[160:161] neg_lo:[0,1] neg_hi:[0,1]
	v_pk_add_f32 v[110:111], v[110:111], v[162:163] neg_lo:[0,1] neg_hi:[0,1]
	v_add_f32_dpp v28, v28, v28 row_ror:8 row_mask:0xf bank_mask:0xf bound_ctrl:1
	v_max_f32_e32 v28, 0x179abe15, v28
	v_rsq_f32_e32 v28, v28
	v_pk_fma_f32 v[110:111], v[8:9], v[110:111], v[162:163]
	v_pk_fma_f32 v[108:109], v[6:7], v[108:109], v[160:161]
	v_pk_mul_f32 v[150:151], v[116:117], v[28:29] op_sel_hi:[1,0] neg_lo:[0,1] neg_hi:[0,1]
	v_lshlrev_b32_e32 v116, 16, v85
	v_and_b32_e32 v117, 0xffff0000, v85
	v_pk_add_f32 v[112:113], v[112:113], v[116:117] neg_lo:[0,1] neg_hi:[0,1]
	v_pk_mul_f32 v[154:155], v[114:115], v[28:29] op_sel_hi:[1,0]
	v_pk_fma_f32 v[158:159], v[12:13], v[112:113], v[116:117]
	v_pk_mul_f32 v[148:149], v[146:147], v[28:29] op_sel_hi:[1,0] neg_lo:[0,1] neg_hi:[0,1]
	v_pk_mul_f32 v[112:113], v[158:159], v[142:143]
	v_fmac_f32_e32 v156, v24, v112
	v_cvt_f32_f16_sdwa v147, v99 dst_sel:DWORD dst_unused:UNUSED_PAD src0_sel:WORD_1
	v_cvt_f32_f16_e32 v146, v99
	v_fmac_f32_e32 v156, v25, v113
	s_nop 1
	v_add_f32_dpp v114, v156, v156 row_ror:1 row_mask:0xf bank_mask:0xf bound_ctrl:1
	s_nop 1
	v_add_f32_dpp v114, v114, v114 row_ror:2 row_mask:0xf bank_mask:0xf bound_ctrl:1
	s_nop 1
	v_add_f32_dpp v112, v114, v114 row_ror:4 row_mask:0xf bank_mask:0xf bound_ctrl:1
	v_mov_b32_e32 v113, 0
	v_pk_add_f32 v[146:147], v[146:147], 1.0 op_sel_hi:[1,0] neg_lo:[1,0] neg_hi:[1,0]
	s_nop 0
	v_mov_b32_dpp v113, v112 row_ror:8 row_mask:0xf bank_mask:0xf
	v_pk_mul_f32 v[152:153], v[152:153], v[28:29] op_sel_hi:[1,0]
	v_pk_mul_f32 v[156:157], v[118:119], 1.0 op_sel_hi:[1,0]
	v_pk_mul_f32 v[158:159], v[158:159], 1.0 op_sel_hi:[1,0]
	ds_write_b128 v129, v[144:147]
	ds_write_b128 v129, v[140:143] offset:256
	ds_write_b128 v129, v[148:151] offset:512
	ds_write_b128 v129, v[152:155] offset:768
	ds_write_b128 v129, v[156:159] offset:1024
	ds_write_b128 v129, v[108:111] offset:1280
	s_and_saveexec_b64 s[56:57], s[4:5]
	s_cbranch_execz .LBB0_1123
	s_or_b64 exec, exec, s[56:57]
	s_and_saveexec_b64 s[56:57], s[44:45]
	s_cbranch_execnz .LBB0_1124
